# FFT fold of w_in Fourier columns moved to f32 MFMA (v_mfma_f32_32x32x2_f32) + sc1 swiglu stores
# speedup vs baseline: 1.0065x; 1.0019x over previous
; #define LAS __attribute__((address_space(3)))
; #define LDS_WAIT() asm volatile("s_waitcnt lgkmcnt(0)" ::: "memory")
; __device__ __forceinline__ void p0a(Frame& F, const Args& AR) {
;     ...
;     {
;         LAS float* scr = (LAS float*)(F.lds + F.wave * 16384);
;         scr[F.lane] = cospif((float)F.lane * (1.0f / 64.0f)); scr[F.lane + 64] = cospif((float)(F.lane + 64) * (1.0f / 64.0f));
;         float* wf = (float*)(ws + WS_WFOLD);
;         for (int it = gw; it < DEPTH * DM * 4; it += NGW) {
;             const int h = it & 3, ld = it >> 2;
;             const float* src = AR.in[I_WIN] + (size_t)ld * DIN + FFT_OFF + 128 * h;
;             LDS_WAIT(); asm volatile("" ::: "memory");
;             scr[128 + F.lane] = src[F.lane]; scr[192 + F.lane] = src[F.lane + 64];
;             LDS_WAIT(); asm volatile("" ::: "memory");
; #pragma unroll
;             for (int q = 0; q < 2; ++q) { const int jj = F.lane + 64 * q, mp = jj >> 1, odd = jj & 1;
;                 const int mult = mp == 0 ? (odd ? 64 : 0) : mp, shift = (mp != 0 && odd) ? 96 : 0; const float sgn = (mp != 0 && odd) ? -1.f : 1.f;
;                 float s = 0.f;
;                 for (int c = 0; c < 128; ++c) s += scr[128 + c] * scr[(mult * c + shift) & 127];
;                 wf[(size_t)ld * 512 + 128 * h + jj] = s * sgn; }
;         }
;         LDS_WAIT(); asm volatile("" ::: "memory");
;     }
.LBB0_32:
	v_readlane_b32 s0, v250, 52
	s_ashr_i32 s12, s0, 6
	s_lshl_b32 s0, s80, 3
	v_or_b32_e32 v2, 64, v66
	s_add_i32 s21, s12, s0
	s_lshl_b32 s1, s12, 14
	v_cvt_f32_ubyte0_e32 v4, v2
	v_cvt_f32_ubyte0_e32 v5, v66
	s_mov_b32 s0, 0x3c800000
	v_pk_mul_f32 v[4:5], v[4:5], s[0:1] op_sel_hi:[1,0]
	s_mov_b32 s0, 0x7f800000
	v_pk_mul_f32 v[8:9], v[4:5], 0.5 op_sel_hi:[1,0]
	v_mov_b32_e32 v11, 0xbf1f24be
	v_fract_f32_e32 v3, v9
	v_add_f32_e32 v3, v3, v3
	v_cmp_neq_f32_e32 vcc, s0, v9
	v_mov_b32_e32 v13, 0x40234736
	v_mov_b32_e32 v14, 0xc0a55e0e
	v_cndmask_b32_e32 v3, 0, v3, vcc
	v_cmp_lt_f32_e32 vcc, 1.0, v5
	v_mov_b32_e32 v16, 0xbfaad1da
	v_mov_b32_e32 v17, 0x4081e0d3
	v_cndmask_b32_e32 v3, v5, v3, vcc
	v_add_f32_e32 v6, v3, v3
	v_rndne_f32_e32 v7, v6
	v_fmac_f32_e32 v3, -0.5, v7
	v_mul_f32_e32 v10, v3, v3
	v_fmamk_f32 v12, v10, 0x3e75aa41, v11
	v_fmaak_f32 v12, v10, v12, 0x40234736
	v_fmaak_f32 v12, v10, v12, 0xc0a55e0e
	v_mul_f32_e32 v15, v3, v10
	v_mul_f32_e32 v12, v15, v12
	v_cvt_i32_f32_e32 v9, v7
	v_fmac_f32_e32 v12, 0x40490fdb, v3
	v_mov_b32_e32 v3, 0x3e642e9d
	v_fmamk_f32 v15, v10, 0x3d4be544, v3
	v_fmaak_f32 v15, v10, v15, 0xbfaad1da
	v_fmaak_f32 v15, v10, v15, 0x4081e0d3
	v_and_b32_e32 v7, 2, v9
	v_fmaak_f32 v15, v10, v15, 0xc09de9e6
	v_and_b32_e32 v9, 1, v9
	v_fma_f32 v10, v10, v15, 1.0
	v_cmp_eq_u32_e32 vcc, 0, v9
	v_mov_b32_e32 v18, 0xc09de9e6
	s_lshl_b32 s20, s33, 3
	v_cndmask_b32_e64 v9, -v12, v10, vcc
	v_cmp_eq_u32_e32 vcc, 0, v7
	v_fract_f32_e32 v10, v8
	v_add_f32_e32 v10, v10, v10
	v_cndmask_b32_e64 v7, -v9, v9, vcc
	v_cmp_neq_f32_e32 vcc, s0, v8
	v_mov_b32_e32 v9, 0x7fc00000
	s_add_i32 s10, s1, 0
	v_cndmask_b32_e32 v8, 0, v10, vcc
	v_cmp_lt_f32_e32 vcc, 1.0, v4
	s_add_u32 s22, s90, 0x700000
	s_addc_u32 s23, s91, 0
	v_cndmask_b32_e32 v8, v4, v8, vcc
	v_add_f32_e32 v10, v8, v8
	v_rndne_f32_e32 v10, v10
	v_fmac_f32_e32 v8, -0.5, v10
	v_cvt_i32_f32_e32 v12, v10
	v_mul_f32_e32 v10, v8, v8
	v_fmac_f32_e32 v11, 0x3e75aa41, v10
	v_fmac_f32_e32 v13, v10, v11
	v_fmac_f32_e32 v3, 0x3d4be544, v10
	v_fmac_f32_e32 v14, v10, v13
	v_mul_f32_e32 v11, v8, v10
	v_fmac_f32_e32 v16, v10, v3
	v_mul_f32_e32 v11, v11, v14
	v_fmac_f32_e32 v17, v10, v16
	v_cmp_lg_f32_e32 vcc, s0, v5
	v_fmac_f32_e32 v11, 0x40490fdb, v8
	v_fmac_f32_e32 v18, v10, v17
	v_and_b32_e32 v8, 1, v12
	v_cndmask_b32_e32 v5, v9, v7, vcc
	v_and_b32_e32 v7, 2, v12
	v_fma_f32 v3, v10, v18, 1.0
	v_cmp_eq_u32_e32 vcc, 0, v8
	v_lshl_add_u32 v6, v66, 2, s10
	s_cmpk_gt_i32 s21, 0x7fff
	v_cndmask_b32_e64 v3, -v11, v3, vcc
	v_cmp_eq_u32_e32 vcc, 0, v7
	s_barrier
	s_nop 0
	v_cndmask_b32_e64 v3, -v3, v3, vcc
	v_cmp_lg_f32_e32 vcc, s0, v4
	s_nop 1
	v_cndmask_b32_e32 v3, v9, v3, vcc
	ds_write2st64_b32 v6, v5, v3 offset1:1
	s_cbranch_scc1 .LBB0_39
	s_cmp_gt_u32 s12, 3
	s_cbranch_scc1 .LBB0_39
	v_readlane_b32 s38, v250, 20
	v_readlane_b32 s39, v250, 21
	s_movk_i32 s11, 0x1fc
	v_and_b32_e32 v7, 31, v66
	v_lshrrev_b32_e32 v8, 5, v66
	s_lshl_b32 s0, s80, 7
	s_lshl_b32 s1, s12, 5
	s_add_i32 s0, s0, s1
	v_add_u32_e32 v9, s0, v7
	v_lshrrev_b32_e32 v10, 2, v9
	v_and_b32_e32 v11, 3, v9
	v_mul_u32_u24_e32 v2, 0x2c00, v10
	v_lshlrev_b32_e32 v12, 9, v11
	v_lshlrev_b32_e32 v13, 8, v8
	v_add3_u32 v2, v2, v12, v13
	v_add_u32_e32 v2, 0x2400, v2
	v_mov_b32_e32 v3, 0
	v_lshl_add_u64 v[246:247], s[38:39], 0, v[2:3]
	v_lshlrev_b32_e32 v4, 9, v9
	v_lshl_add_u32 v4, v8, 4, v4
	v_mov_b32_e32 v5, 0
	v_lshl_add_u64 v[248:249], s[22:23], 0, v[4:5]
	global_load_dwordx4 v[160:163], v[246:247], off
	global_load_dwordx4 v[164:167], v[246:247], off offset:16
	global_load_dwordx4 v[168:171], v[246:247], off offset:32
	global_load_dwordx4 v[172:175], v[246:247], off offset:48
	global_load_dwordx4 v[176:179], v[246:247], off offset:64
	global_load_dwordx4 v[180:183], v[246:247], off offset:80
	global_load_dwordx4 v[184:187], v[246:247], off offset:96
	global_load_dwordx4 v[188:191], v[246:247], off offset:112
	global_load_dwordx4 v[192:195], v[246:247], off offset:128
	global_load_dwordx4 v[196:199], v[246:247], off offset:144
	global_load_dwordx4 v[200:203], v[246:247], off offset:160
	global_load_dwordx4 v[204:207], v[246:247], off offset:176
	global_load_dwordx4 v[208:211], v[246:247], off offset:192
	global_load_dwordx4 v[212:215], v[246:247], off offset:208
	global_load_dwordx4 v[216:219], v[246:247], off offset:224
	global_load_dwordx4 v[220:223], v[246:247], off offset:240
	v_mov_b32_e32 v244, s10
	v_lshlrev_b32_e32 v14, 6, v8
	v_add_u32_e32 v15, 0, v7
	v_lshrrev_b32_e32 v16, 1, v15
	v_and_b32_e32 v17, 1, v15
	v_lshlrev_b32_e32 v18, 6, v17
	v_lshlrev_b32_e32 v19, 7, v17
	v_cmp_eq_u32_e32 vcc, 0, v16
	s_nop 1
	v_cndmask_b32_e32 v16, v16, v18, vcc
	v_cndmask_b32_e64 v19, v19, 0, vcc
	v_lshlrev_b32_e32 v236, 2, v16
	v_mad_u32_u24 v232, v236, v14, v19
	v_add_u32_e32 v15, 32, v7
	v_lshrrev_b32_e32 v16, 1, v15
	v_and_b32_e32 v17, 1, v15
	v_lshlrev_b32_e32 v18, 6, v17
	v_lshlrev_b32_e32 v19, 7, v17
	v_cmp_eq_u32_e32 vcc, 0, v16
	s_nop 1
	v_cndmask_b32_e32 v16, v16, v18, vcc
	v_cndmask_b32_e64 v19, v19, 0, vcc
	v_lshlrev_b32_e32 v237, 2, v16
	v_mad_u32_u24 v233, v237, v14, v19
	v_add_u32_e32 v15, 64, v7
	v_lshrrev_b32_e32 v16, 1, v15
	v_and_b32_e32 v17, 1, v15
	v_lshlrev_b32_e32 v18, 6, v17
	v_lshlrev_b32_e32 v19, 7, v17
	v_cmp_eq_u32_e32 vcc, 0, v16
	s_nop 1
	v_cndmask_b32_e32 v16, v16, v18, vcc
	v_cndmask_b32_e64 v19, v19, 0, vcc
	v_lshlrev_b32_e32 v238, 2, v16
	v_mad_u32_u24 v234, v238, v14, v19
	v_add_u32_e32 v15, 96, v7
	v_lshrrev_b32_e32 v16, 1, v15
	v_and_b32_e32 v17, 1, v15
	v_lshlrev_b32_e32 v18, 6, v17
	v_lshlrev_b32_e32 v19, 7, v17
	v_cmp_eq_u32_e32 vcc, 0, v16
	s_nop 1
	v_cndmask_b32_e32 v16, v16, v18, vcc
	v_cndmask_b32_e64 v19, v19, 0, vcc
	v_lshlrev_b32_e32 v239, 2, v16
	v_mad_u32_u24 v235, v239, v14, v19
	v_and_or_b32 v240, v232, s11, v244
	v_and_or_b32 v241, v233, s11, v244
	v_and_or_b32 v242, v234, s11, v244
	v_and_or_b32 v243, v235, s11, v244
	ds_read_b32 v224, v240
	ds_read_b32 v225, v241
	ds_read_b32 v226, v242
	ds_read_b32 v227, v243
	v_add_u32_e32 v232, v232, v236
	v_and_or_b32 v240, v232, s11, v244
	v_add_u32_e32 v233, v233, v237
	v_and_or_b32 v241, v233, s11, v244
	v_add_u32_e32 v234, v234, v238
	v_and_or_b32 v242, v234, s11, v244
	v_add_u32_e32 v235, v235, v239
	v_and_or_b32 v243, v235, s11, v244
	ds_read_b32 v228, v240
	ds_read_b32 v229, v241
	ds_read_b32 v230, v242
	ds_read_b32 v231, v243
	s_waitcnt vmcnt(15) lgkmcnt(4)
; __device__ __forceinline__ void p0a(Frame& F, const Args& AR) {
;     ...
;             for (int q = 0; q < 2; ++q) { const int jj = F.lane + 64 * q, mp = jj >> 1, odd = jj & 1;
;                 const int mult = mp == 0 ? (odd ? 64 : 0) : mp, shift = (mp != 0 && odd) ? 96 : 0; const float sgn = (mp != 0 && odd) ? -1.f : 1.f;
;                 float s = 0.f;
;                 for (int c = 0; c < 128; ++c) s += scr[128 + c] * scr[(mult * c + shift) & 127];
;                 wf[(size_t)ld * 512 + 128 * h + jj] = s * sgn; }
	v_mfma_f32_32x32x2_f32 v[96:111], v224, v160, 0
	v_mfma_f32_32x32x2_f32 v[112:127], v225, v160, 0
	v_mfma_f32_32x32x2_f32 v[128:143], v226, v160, 0
	v_mfma_f32_32x32x2_f32 v[144:159], v227, v160, 0
	v_add_u32_e32 v232, v232, v236
	v_and_or_b32 v240, v232, s11, v244
	v_add_u32_e32 v233, v233, v237
	v_and_or_b32 v241, v233, s11, v244
	v_add_u32_e32 v234, v234, v238
	v_and_or_b32 v242, v234, s11, v244
	v_add_u32_e32 v235, v235, v239
	v_and_or_b32 v243, v235, s11, v244
	ds_read_b32 v224, v240
	ds_read_b32 v225, v241
	ds_read_b32 v226, v242
	ds_read_b32 v227, v243
	s_waitcnt lgkmcnt(4)
	v_mfma_f32_32x32x2_f32 v[96:111], v228, v161, v[96:111]
	v_mfma_f32_32x32x2_f32 v[112:127], v229, v161, v[112:127]
	v_mfma_f32_32x32x2_f32 v[128:143], v230, v161, v[128:143]
	v_mfma_f32_32x32x2_f32 v[144:159], v231, v161, v[144:159]
	v_add_u32_e32 v232, v232, v236
	v_and_or_b32 v240, v232, s11, v244
	v_add_u32_e32 v233, v233, v237
	v_and_or_b32 v241, v233, s11, v244
	v_add_u32_e32 v234, v234, v238
	v_and_or_b32 v242, v234, s11, v244
	v_add_u32_e32 v235, v235, v239
	v_and_or_b32 v243, v235, s11, v244
	ds_read_b32 v228, v240
	ds_read_b32 v229, v241
	ds_read_b32 v230, v242
	ds_read_b32 v231, v243
	s_waitcnt lgkmcnt(4)
	v_mfma_f32_32x32x2_f32 v[96:111], v224, v162, v[96:111]
	v_mfma_f32_32x32x2_f32 v[112:127], v225, v162, v[112:127]
	v_mfma_f32_32x32x2_f32 v[128:143], v226, v162, v[128:143]
	v_mfma_f32_32x32x2_f32 v[144:159], v227, v162, v[144:159]
	v_add_u32_e32 v232, v232, v236
	v_and_or_b32 v240, v232, s11, v244
	v_add_u32_e32 v233, v233, v237
	v_and_or_b32 v241, v233, s11, v244
	v_add_u32_e32 v234, v234, v238
	v_and_or_b32 v242, v234, s11, v244
	v_add_u32_e32 v235, v235, v239
	v_and_or_b32 v243, v235, s11, v244
	ds_read_b32 v224, v240
	ds_read_b32 v225, v241
	ds_read_b32 v226, v242
	ds_read_b32 v227, v243
	s_waitcnt lgkmcnt(4)
	v_mfma_f32_32x32x2_f32 v[96:111], v228, v163, v[96:111]
	v_mfma_f32_32x32x2_f32 v[112:127], v229, v163, v[112:127]
	v_mfma_f32_32x32x2_f32 v[128:143], v230, v163, v[128:143]
	v_mfma_f32_32x32x2_f32 v[144:159], v231, v163, v[144:159]
	v_add_u32_e32 v232, v232, v236
	v_and_or_b32 v240, v232, s11, v244
	v_add_u32_e32 v233, v233, v237
	v_and_or_b32 v241, v233, s11, v244
	v_add_u32_e32 v234, v234, v238
	v_and_or_b32 v242, v234, s11, v244
	v_add_u32_e32 v235, v235, v239
	v_and_or_b32 v243, v235, s11, v244
	ds_read_b32 v228, v240
	ds_read_b32 v229, v241
	ds_read_b32 v230, v242
	ds_read_b32 v231, v243
	s_waitcnt vmcnt(14) lgkmcnt(4)
	v_mfma_f32_32x32x2_f32 v[96:111], v224, v164, v[96:111]
	v_mfma_f32_32x32x2_f32 v[112:127], v225, v164, v[112:127]
	v_mfma_f32_32x32x2_f32 v[128:143], v226, v164, v[128:143]
	v_mfma_f32_32x32x2_f32 v[144:159], v227, v164, v[144:159]
	v_add_u32_e32 v232, v232, v236
	v_and_or_b32 v240, v232, s11, v244
	v_add_u32_e32 v233, v233, v237
	v_and_or_b32 v241, v233, s11, v244
	v_add_u32_e32 v234, v234, v238
	v_and_or_b32 v242, v234, s11, v244
	v_add_u32_e32 v235, v235, v239
	v_and_or_b32 v243, v235, s11, v244
	ds_read_b32 v224, v240
	ds_read_b32 v225, v241
	ds_read_b32 v226, v242
	ds_read_b32 v227, v243
	s_waitcnt lgkmcnt(4)
	v_mfma_f32_32x32x2_f32 v[96:111], v228, v165, v[96:111]
	v_mfma_f32_32x32x2_f32 v[112:127], v229, v165, v[112:127]
	v_mfma_f32_32x32x2_f32 v[128:143], v230, v165, v[128:143]
	v_mfma_f32_32x32x2_f32 v[144:159], v231, v165, v[144:159]
	v_add_u32_e32 v232, v232, v236
	v_and_or_b32 v240, v232, s11, v244
	v_add_u32_e32 v233, v233, v237
	v_and_or_b32 v241, v233, s11, v244
	v_add_u32_e32 v234, v234, v238
	v_and_or_b32 v242, v234, s11, v244
	v_add_u32_e32 v235, v235, v239
	v_and_or_b32 v243, v235, s11, v244
	ds_read_b32 v228, v240
	ds_read_b32 v229, v241
	ds_read_b32 v230, v242
	ds_read_b32 v231, v243
	s_waitcnt lgkmcnt(4)
	v_mfma_f32_32x32x2_f32 v[96:111], v224, v166, v[96:111]
	v_mfma_f32_32x32x2_f32 v[112:127], v225, v166, v[112:127]
	v_mfma_f32_32x32x2_f32 v[128:143], v226, v166, v[128:143]
	v_mfma_f32_32x32x2_f32 v[144:159], v227, v166, v[144:159]
	v_add_u32_e32 v232, v232, v236
	v_and_or_b32 v240, v232, s11, v244
	v_add_u32_e32 v233, v233, v237
	v_and_or_b32 v241, v233, s11, v244
	v_add_u32_e32 v234, v234, v238
	v_and_or_b32 v242, v234, s11, v244
	v_add_u32_e32 v235, v235, v239
	v_and_or_b32 v243, v235, s11, v244
	ds_read_b32 v224, v240
	ds_read_b32 v225, v241
	ds_read_b32 v226, v242
	ds_read_b32 v227, v243
	s_waitcnt lgkmcnt(4)
	v_mfma_f32_32x32x2_f32 v[96:111], v228, v167, v[96:111]
	v_mfma_f32_32x32x2_f32 v[112:127], v229, v167, v[112:127]
	v_mfma_f32_32x32x2_f32 v[128:143], v230, v167, v[128:143]
	v_mfma_f32_32x32x2_f32 v[144:159], v231, v167, v[144:159]
	v_add_u32_e32 v232, v232, v236
	v_and_or_b32 v240, v232, s11, v244
	v_add_u32_e32 v233, v233, v237
	v_and_or_b32 v241, v233, s11, v244
	v_add_u32_e32 v234, v234, v238
	v_and_or_b32 v242, v234, s11, v244
	v_add_u32_e32 v235, v235, v239
	v_and_or_b32 v243, v235, s11, v244
	ds_read_b32 v228, v240
	ds_read_b32 v229, v241
	ds_read_b32 v230, v242
	ds_read_b32 v231, v243
	s_waitcnt vmcnt(13) lgkmcnt(4)
	v_mfma_f32_32x32x2_f32 v[96:111], v224, v168, v[96:111]
	v_mfma_f32_32x32x2_f32 v[112:127], v225, v168, v[112:127]
	v_mfma_f32_32x32x2_f32 v[128:143], v226, v168, v[128:143]
	v_mfma_f32_32x32x2_f32 v[144:159], v227, v168, v[144:159]
	v_add_u32_e32 v232, v232, v236
	v_and_or_b32 v240, v232, s11, v244
	v_add_u32_e32 v233, v233, v237
	v_and_or_b32 v241, v233, s11, v244
	v_add_u32_e32 v234, v234, v238
	v_and_or_b32 v242, v234, s11, v244
	v_add_u32_e32 v235, v235, v239
	v_and_or_b32 v243, v235, s11, v244
	ds_read_b32 v224, v240
	ds_read_b32 v225, v241
	ds_read_b32 v226, v242
	ds_read_b32 v227, v243
	s_waitcnt lgkmcnt(4)
; __device__ __forceinline__ void p0a(Frame& F, const Args& AR) {
;     ...
;             for (int q = 0; q < 2; ++q) { const int jj = F.lane + 64 * q, mp = jj >> 1, odd = jj & 1;
;                 const int mult = mp == 0 ? (odd ? 64 : 0) : mp, shift = (mp != 0 && odd) ? 96 : 0; const float sgn = (mp != 0 && odd) ? -1.f : 1.f;
;                 float s = 0.f;
;                 for (int c = 0; c < 128; ++c) s += scr[128 + c] * scr[(mult * c + shift) & 127];
;                 wf[(size_t)ld * 512 + 128 * h + jj] = s * sgn; }
	v_mfma_f32_32x32x2_f32 v[96:111], v228, v169, v[96:111]
	v_mfma_f32_32x32x2_f32 v[112:127], v229, v169, v[112:127]
	v_mfma_f32_32x32x2_f32 v[128:143], v230, v169, v[128:143]
	v_mfma_f32_32x32x2_f32 v[144:159], v231, v169, v[144:159]
	v_add_u32_e32 v232, v232, v236
	v_and_or_b32 v240, v232, s11, v244
	v_add_u32_e32 v233, v233, v237
	v_and_or_b32 v241, v233, s11, v244
	v_add_u32_e32 v234, v234, v238
	v_and_or_b32 v242, v234, s11, v244
	v_add_u32_e32 v235, v235, v239
	v_and_or_b32 v243, v235, s11, v244
	ds_read_b32 v228, v240
	ds_read_b32 v229, v241
	ds_read_b32 v230, v242
	ds_read_b32 v231, v243
	s_waitcnt lgkmcnt(4)
	v_mfma_f32_32x32x2_f32 v[96:111], v224, v170, v[96:111]
	v_mfma_f32_32x32x2_f32 v[112:127], v225, v170, v[112:127]
	v_mfma_f32_32x32x2_f32 v[128:143], v226, v170, v[128:143]
	v_mfma_f32_32x32x2_f32 v[144:159], v227, v170, v[144:159]
	v_add_u32_e32 v232, v232, v236
	v_and_or_b32 v240, v232, s11, v244
	v_add_u32_e32 v233, v233, v237
	v_and_or_b32 v241, v233, s11, v244
	v_add_u32_e32 v234, v234, v238
	v_and_or_b32 v242, v234, s11, v244
	v_add_u32_e32 v235, v235, v239
	v_and_or_b32 v243, v235, s11, v244
	ds_read_b32 v224, v240
	ds_read_b32 v225, v241
	ds_read_b32 v226, v242
	ds_read_b32 v227, v243
	s_waitcnt lgkmcnt(4)
	v_mfma_f32_32x32x2_f32 v[96:111], v228, v171, v[96:111]
	v_mfma_f32_32x32x2_f32 v[112:127], v229, v171, v[112:127]
	v_mfma_f32_32x32x2_f32 v[128:143], v230, v171, v[128:143]
	v_mfma_f32_32x32x2_f32 v[144:159], v231, v171, v[144:159]
	v_add_u32_e32 v232, v232, v236
	v_and_or_b32 v240, v232, s11, v244
	v_add_u32_e32 v233, v233, v237
	v_and_or_b32 v241, v233, s11, v244
	v_add_u32_e32 v234, v234, v238
	v_and_or_b32 v242, v234, s11, v244
	v_add_u32_e32 v235, v235, v239
	v_and_or_b32 v243, v235, s11, v244
	ds_read_b32 v228, v240
	ds_read_b32 v229, v241
	ds_read_b32 v230, v242
	ds_read_b32 v231, v243
	s_waitcnt vmcnt(12) lgkmcnt(4)
	v_mfma_f32_32x32x2_f32 v[96:111], v224, v172, v[96:111]
	v_mfma_f32_32x32x2_f32 v[112:127], v225, v172, v[112:127]
	v_mfma_f32_32x32x2_f32 v[128:143], v226, v172, v[128:143]
	v_mfma_f32_32x32x2_f32 v[144:159], v227, v172, v[144:159]
	v_add_u32_e32 v232, v232, v236
	v_and_or_b32 v240, v232, s11, v244
	v_add_u32_e32 v233, v233, v237
	v_and_or_b32 v241, v233, s11, v244
	v_add_u32_e32 v234, v234, v238
	v_and_or_b32 v242, v234, s11, v244
	v_add_u32_e32 v235, v235, v239
	v_and_or_b32 v243, v235, s11, v244
	ds_read_b32 v224, v240
	ds_read_b32 v225, v241
	ds_read_b32 v226, v242
	ds_read_b32 v227, v243
	s_waitcnt lgkmcnt(4)
	v_mfma_f32_32x32x2_f32 v[96:111], v228, v173, v[96:111]
	v_mfma_f32_32x32x2_f32 v[112:127], v229, v173, v[112:127]
	v_mfma_f32_32x32x2_f32 v[128:143], v230, v173, v[128:143]
	v_mfma_f32_32x32x2_f32 v[144:159], v231, v173, v[144:159]
	v_add_u32_e32 v232, v232, v236
	v_and_or_b32 v240, v232, s11, v244
	v_add_u32_e32 v233, v233, v237
	v_and_or_b32 v241, v233, s11, v244
	v_add_u32_e32 v234, v234, v238
	v_and_or_b32 v242, v234, s11, v244
	v_add_u32_e32 v235, v235, v239
	v_and_or_b32 v243, v235, s11, v244
	ds_read_b32 v228, v240
	ds_read_b32 v229, v241
	ds_read_b32 v230, v242
	ds_read_b32 v231, v243
	s_waitcnt lgkmcnt(4)
	v_mfma_f32_32x32x2_f32 v[96:111], v224, v174, v[96:111]
	v_mfma_f32_32x32x2_f32 v[112:127], v225, v174, v[112:127]
	v_mfma_f32_32x32x2_f32 v[128:143], v226, v174, v[128:143]
	v_mfma_f32_32x32x2_f32 v[144:159], v227, v174, v[144:159]
	v_add_u32_e32 v232, v232, v236
	v_and_or_b32 v240, v232, s11, v244
	v_add_u32_e32 v233, v233, v237
	v_and_or_b32 v241, v233, s11, v244
	v_add_u32_e32 v234, v234, v238
	v_and_or_b32 v242, v234, s11, v244
	v_add_u32_e32 v235, v235, v239
	v_and_or_b32 v243, v235, s11, v244
	ds_read_b32 v224, v240
	ds_read_b32 v225, v241
	ds_read_b32 v226, v242
	ds_read_b32 v227, v243
	s_waitcnt lgkmcnt(4)
	v_mfma_f32_32x32x2_f32 v[96:111], v228, v175, v[96:111]
	v_mfma_f32_32x32x2_f32 v[112:127], v229, v175, v[112:127]
	v_mfma_f32_32x32x2_f32 v[128:143], v230, v175, v[128:143]
	v_mfma_f32_32x32x2_f32 v[144:159], v231, v175, v[144:159]
	v_add_u32_e32 v232, v232, v236
	v_and_or_b32 v240, v232, s11, v244
	v_add_u32_e32 v233, v233, v237
	v_and_or_b32 v241, v233, s11, v244
	v_add_u32_e32 v234, v234, v238
	v_and_or_b32 v242, v234, s11, v244
	v_add_u32_e32 v235, v235, v239
	v_and_or_b32 v243, v235, s11, v244
	ds_read_b32 v228, v240
	ds_read_b32 v229, v241
	ds_read_b32 v230, v242
	ds_read_b32 v231, v243
	s_waitcnt vmcnt(11) lgkmcnt(4)
	v_mfma_f32_32x32x2_f32 v[96:111], v224, v176, v[96:111]
	v_mfma_f32_32x32x2_f32 v[112:127], v225, v176, v[112:127]
	v_mfma_f32_32x32x2_f32 v[128:143], v226, v176, v[128:143]
	v_mfma_f32_32x32x2_f32 v[144:159], v227, v176, v[144:159]
	v_add_u32_e32 v232, v232, v236
	v_and_or_b32 v240, v232, s11, v244
	v_add_u32_e32 v233, v233, v237
	v_and_or_b32 v241, v233, s11, v244
	v_add_u32_e32 v234, v234, v238
	v_and_or_b32 v242, v234, s11, v244
	v_add_u32_e32 v235, v235, v239
	v_and_or_b32 v243, v235, s11, v244
	ds_read_b32 v224, v240
	ds_read_b32 v225, v241
	ds_read_b32 v226, v242
	ds_read_b32 v227, v243
	s_waitcnt lgkmcnt(4)
	v_mfma_f32_32x32x2_f32 v[96:111], v228, v177, v[96:111]
	v_mfma_f32_32x32x2_f32 v[112:127], v229, v177, v[112:127]
	v_mfma_f32_32x32x2_f32 v[128:143], v230, v177, v[128:143]
	v_mfma_f32_32x32x2_f32 v[144:159], v231, v177, v[144:159]
	v_add_u32_e32 v232, v232, v236
	v_and_or_b32 v240, v232, s11, v244
	v_add_u32_e32 v233, v233, v237
	v_and_or_b32 v241, v233, s11, v244
	v_add_u32_e32 v234, v234, v238
	v_and_or_b32 v242, v234, s11, v244
	v_add_u32_e32 v235, v235, v239
	v_and_or_b32 v243, v235, s11, v244
	ds_read_b32 v228, v240
	ds_read_b32 v229, v241
	ds_read_b32 v230, v242
	ds_read_b32 v231, v243
	s_waitcnt lgkmcnt(4)
; __device__ __forceinline__ void p0a(Frame& F, const Args& AR) {
;     ...
;             for (int q = 0; q < 2; ++q) { const int jj = F.lane + 64 * q, mp = jj >> 1, odd = jj & 1;
;                 const int mult = mp == 0 ? (odd ? 64 : 0) : mp, shift = (mp != 0 && odd) ? 96 : 0; const float sgn = (mp != 0 && odd) ? -1.f : 1.f;
;                 float s = 0.f;
;                 for (int c = 0; c < 128; ++c) s += scr[128 + c] * scr[(mult * c + shift) & 127];
;                 wf[(size_t)ld * 512 + 128 * h + jj] = s * sgn; }
	v_mfma_f32_32x32x2_f32 v[96:111], v224, v178, v[96:111]
	v_mfma_f32_32x32x2_f32 v[112:127], v225, v178, v[112:127]
	v_mfma_f32_32x32x2_f32 v[128:143], v226, v178, v[128:143]
	v_mfma_f32_32x32x2_f32 v[144:159], v227, v178, v[144:159]
	v_add_u32_e32 v232, v232, v236
	v_and_or_b32 v240, v232, s11, v244
	v_add_u32_e32 v233, v233, v237
	v_and_or_b32 v241, v233, s11, v244
	v_add_u32_e32 v234, v234, v238
	v_and_or_b32 v242, v234, s11, v244
	v_add_u32_e32 v235, v235, v239
	v_and_or_b32 v243, v235, s11, v244
	ds_read_b32 v224, v240
	ds_read_b32 v225, v241
	ds_read_b32 v226, v242
	ds_read_b32 v227, v243
	s_waitcnt lgkmcnt(4)
	v_mfma_f32_32x32x2_f32 v[96:111], v228, v179, v[96:111]
	v_mfma_f32_32x32x2_f32 v[112:127], v229, v179, v[112:127]
	v_mfma_f32_32x32x2_f32 v[128:143], v230, v179, v[128:143]
	v_mfma_f32_32x32x2_f32 v[144:159], v231, v179, v[144:159]
	v_add_u32_e32 v232, v232, v236
	v_and_or_b32 v240, v232, s11, v244
	v_add_u32_e32 v233, v233, v237
	v_and_or_b32 v241, v233, s11, v244
	v_add_u32_e32 v234, v234, v238
	v_and_or_b32 v242, v234, s11, v244
	v_add_u32_e32 v235, v235, v239
	v_and_or_b32 v243, v235, s11, v244
	ds_read_b32 v228, v240
	ds_read_b32 v229, v241
	ds_read_b32 v230, v242
	ds_read_b32 v231, v243
	s_waitcnt vmcnt(10) lgkmcnt(4)
	v_mfma_f32_32x32x2_f32 v[96:111], v224, v180, v[96:111]
	v_mfma_f32_32x32x2_f32 v[112:127], v225, v180, v[112:127]
	v_mfma_f32_32x32x2_f32 v[128:143], v226, v180, v[128:143]
	v_mfma_f32_32x32x2_f32 v[144:159], v227, v180, v[144:159]
	v_add_u32_e32 v232, v232, v236
	v_and_or_b32 v240, v232, s11, v244
	v_add_u32_e32 v233, v233, v237
	v_and_or_b32 v241, v233, s11, v244
	v_add_u32_e32 v234, v234, v238
	v_and_or_b32 v242, v234, s11, v244
	v_add_u32_e32 v235, v235, v239
	v_and_or_b32 v243, v235, s11, v244
	ds_read_b32 v224, v240
	ds_read_b32 v225, v241
	ds_read_b32 v226, v242
	ds_read_b32 v227, v243
	s_waitcnt lgkmcnt(4)
	v_mfma_f32_32x32x2_f32 v[96:111], v228, v181, v[96:111]
	v_mfma_f32_32x32x2_f32 v[112:127], v229, v181, v[112:127]
	v_mfma_f32_32x32x2_f32 v[128:143], v230, v181, v[128:143]
	v_mfma_f32_32x32x2_f32 v[144:159], v231, v181, v[144:159]
	v_add_u32_e32 v232, v232, v236
	v_and_or_b32 v240, v232, s11, v244
	v_add_u32_e32 v233, v233, v237
	v_and_or_b32 v241, v233, s11, v244
	v_add_u32_e32 v234, v234, v238
	v_and_or_b32 v242, v234, s11, v244
	v_add_u32_e32 v235, v235, v239
	v_and_or_b32 v243, v235, s11, v244
	ds_read_b32 v228, v240
	ds_read_b32 v229, v241
	ds_read_b32 v230, v242
	ds_read_b32 v231, v243
	s_waitcnt lgkmcnt(4)
	v_mfma_f32_32x32x2_f32 v[96:111], v224, v182, v[96:111]
	v_mfma_f32_32x32x2_f32 v[112:127], v225, v182, v[112:127]
	v_mfma_f32_32x32x2_f32 v[128:143], v226, v182, v[128:143]
	v_mfma_f32_32x32x2_f32 v[144:159], v227, v182, v[144:159]
	v_add_u32_e32 v232, v232, v236
	v_and_or_b32 v240, v232, s11, v244
	v_add_u32_e32 v233, v233, v237
	v_and_or_b32 v241, v233, s11, v244
	v_add_u32_e32 v234, v234, v238
	v_and_or_b32 v242, v234, s11, v244
	v_add_u32_e32 v235, v235, v239
	v_and_or_b32 v243, v235, s11, v244
	ds_read_b32 v224, v240
	ds_read_b32 v225, v241
	ds_read_b32 v226, v242
	ds_read_b32 v227, v243
	s_waitcnt lgkmcnt(4)
	v_mfma_f32_32x32x2_f32 v[96:111], v228, v183, v[96:111]
	v_mfma_f32_32x32x2_f32 v[112:127], v229, v183, v[112:127]
	v_mfma_f32_32x32x2_f32 v[128:143], v230, v183, v[128:143]
	v_mfma_f32_32x32x2_f32 v[144:159], v231, v183, v[144:159]
	v_add_u32_e32 v232, v232, v236
	v_and_or_b32 v240, v232, s11, v244
	v_add_u32_e32 v233, v233, v237
	v_and_or_b32 v241, v233, s11, v244
	v_add_u32_e32 v234, v234, v238
	v_and_or_b32 v242, v234, s11, v244
	v_add_u32_e32 v235, v235, v239
	v_and_or_b32 v243, v235, s11, v244
	ds_read_b32 v228, v240
	ds_read_b32 v229, v241
	ds_read_b32 v230, v242
	ds_read_b32 v231, v243
	s_waitcnt vmcnt(9) lgkmcnt(4)
	v_mfma_f32_32x32x2_f32 v[96:111], v224, v184, v[96:111]
	v_mfma_f32_32x32x2_f32 v[112:127], v225, v184, v[112:127]
	v_mfma_f32_32x32x2_f32 v[128:143], v226, v184, v[128:143]
	v_mfma_f32_32x32x2_f32 v[144:159], v227, v184, v[144:159]
	v_add_u32_e32 v232, v232, v236
	v_and_or_b32 v240, v232, s11, v244
	v_add_u32_e32 v233, v233, v237
	v_and_or_b32 v241, v233, s11, v244
	v_add_u32_e32 v234, v234, v238
	v_and_or_b32 v242, v234, s11, v244
	v_add_u32_e32 v235, v235, v239
	v_and_or_b32 v243, v235, s11, v244
	ds_read_b32 v224, v240
	ds_read_b32 v225, v241
	ds_read_b32 v226, v242
	ds_read_b32 v227, v243
	s_waitcnt lgkmcnt(4)
	v_mfma_f32_32x32x2_f32 v[96:111], v228, v185, v[96:111]
	v_mfma_f32_32x32x2_f32 v[112:127], v229, v185, v[112:127]
	v_mfma_f32_32x32x2_f32 v[128:143], v230, v185, v[128:143]
	v_mfma_f32_32x32x2_f32 v[144:159], v231, v185, v[144:159]
	v_add_u32_e32 v232, v232, v236
	v_and_or_b32 v240, v232, s11, v244
	v_add_u32_e32 v233, v233, v237
	v_and_or_b32 v241, v233, s11, v244
	v_add_u32_e32 v234, v234, v238
	v_and_or_b32 v242, v234, s11, v244
	v_add_u32_e32 v235, v235, v239
	v_and_or_b32 v243, v235, s11, v244
	ds_read_b32 v228, v240
	ds_read_b32 v229, v241
	ds_read_b32 v230, v242
	ds_read_b32 v231, v243
	s_waitcnt lgkmcnt(4)
	v_mfma_f32_32x32x2_f32 v[96:111], v224, v186, v[96:111]
	v_mfma_f32_32x32x2_f32 v[112:127], v225, v186, v[112:127]
	v_mfma_f32_32x32x2_f32 v[128:143], v226, v186, v[128:143]
	v_mfma_f32_32x32x2_f32 v[144:159], v227, v186, v[144:159]
	v_add_u32_e32 v232, v232, v236
	v_and_or_b32 v240, v232, s11, v244
	v_add_u32_e32 v233, v233, v237
	v_and_or_b32 v241, v233, s11, v244
	v_add_u32_e32 v234, v234, v238
	v_and_or_b32 v242, v234, s11, v244
	v_add_u32_e32 v235, v235, v239
	v_and_or_b32 v243, v235, s11, v244
	ds_read_b32 v224, v240
	ds_read_b32 v225, v241
	ds_read_b32 v226, v242
	ds_read_b32 v227, v243
	s_waitcnt lgkmcnt(4)
; __device__ __forceinline__ void p0a(Frame& F, const Args& AR) {
;     ...
;             for (int q = 0; q < 2; ++q) { const int jj = F.lane + 64 * q, mp = jj >> 1, odd = jj & 1;
;                 const int mult = mp == 0 ? (odd ? 64 : 0) : mp, shift = (mp != 0 && odd) ? 96 : 0; const float sgn = (mp != 0 && odd) ? -1.f : 1.f;
;                 float s = 0.f;
;                 for (int c = 0; c < 128; ++c) s += scr[128 + c] * scr[(mult * c + shift) & 127];
;                 wf[(size_t)ld * 512 + 128 * h + jj] = s * sgn; }
	v_mfma_f32_32x32x2_f32 v[96:111], v228, v187, v[96:111]
	v_mfma_f32_32x32x2_f32 v[112:127], v229, v187, v[112:127]
	v_mfma_f32_32x32x2_f32 v[128:143], v230, v187, v[128:143]
	v_mfma_f32_32x32x2_f32 v[144:159], v231, v187, v[144:159]
	v_add_u32_e32 v232, v232, v236
	v_and_or_b32 v240, v232, s11, v244
	v_add_u32_e32 v233, v233, v237
	v_and_or_b32 v241, v233, s11, v244
	v_add_u32_e32 v234, v234, v238
	v_and_or_b32 v242, v234, s11, v244
	v_add_u32_e32 v235, v235, v239
	v_and_or_b32 v243, v235, s11, v244
	ds_read_b32 v228, v240
	ds_read_b32 v229, v241
	ds_read_b32 v230, v242
	ds_read_b32 v231, v243
	s_waitcnt vmcnt(8) lgkmcnt(4)
	v_mfma_f32_32x32x2_f32 v[96:111], v224, v188, v[96:111]
	v_mfma_f32_32x32x2_f32 v[112:127], v225, v188, v[112:127]
	v_mfma_f32_32x32x2_f32 v[128:143], v226, v188, v[128:143]
	v_mfma_f32_32x32x2_f32 v[144:159], v227, v188, v[144:159]
	v_add_u32_e32 v232, v232, v236
	v_and_or_b32 v240, v232, s11, v244
	v_add_u32_e32 v233, v233, v237
	v_and_or_b32 v241, v233, s11, v244
	v_add_u32_e32 v234, v234, v238
	v_and_or_b32 v242, v234, s11, v244
	v_add_u32_e32 v235, v235, v239
	v_and_or_b32 v243, v235, s11, v244
	ds_read_b32 v224, v240
	ds_read_b32 v225, v241
	ds_read_b32 v226, v242
	ds_read_b32 v227, v243
	s_waitcnt lgkmcnt(4)
	v_mfma_f32_32x32x2_f32 v[96:111], v228, v189, v[96:111]
	v_mfma_f32_32x32x2_f32 v[112:127], v229, v189, v[112:127]
	v_mfma_f32_32x32x2_f32 v[128:143], v230, v189, v[128:143]
	v_mfma_f32_32x32x2_f32 v[144:159], v231, v189, v[144:159]
	v_add_u32_e32 v232, v232, v236
	v_and_or_b32 v240, v232, s11, v244
	v_add_u32_e32 v233, v233, v237
	v_and_or_b32 v241, v233, s11, v244
	v_add_u32_e32 v234, v234, v238
	v_and_or_b32 v242, v234, s11, v244
	v_add_u32_e32 v235, v235, v239
	v_and_or_b32 v243, v235, s11, v244
	ds_read_b32 v228, v240
	ds_read_b32 v229, v241
	ds_read_b32 v230, v242
	ds_read_b32 v231, v243
	s_waitcnt lgkmcnt(4)
	v_mfma_f32_32x32x2_f32 v[96:111], v224, v190, v[96:111]
	v_mfma_f32_32x32x2_f32 v[112:127], v225, v190, v[112:127]
	v_mfma_f32_32x32x2_f32 v[128:143], v226, v190, v[128:143]
	v_mfma_f32_32x32x2_f32 v[144:159], v227, v190, v[144:159]
	v_add_u32_e32 v232, v232, v236
	v_and_or_b32 v240, v232, s11, v244
	v_add_u32_e32 v233, v233, v237
	v_and_or_b32 v241, v233, s11, v244
	v_add_u32_e32 v234, v234, v238
	v_and_or_b32 v242, v234, s11, v244
	v_add_u32_e32 v235, v235, v239
	v_and_or_b32 v243, v235, s11, v244
	ds_read_b32 v224, v240
	ds_read_b32 v225, v241
	ds_read_b32 v226, v242
	ds_read_b32 v227, v243
	s_waitcnt lgkmcnt(4)
	v_mfma_f32_32x32x2_f32 v[96:111], v228, v191, v[96:111]
	v_mfma_f32_32x32x2_f32 v[112:127], v229, v191, v[112:127]
	v_mfma_f32_32x32x2_f32 v[128:143], v230, v191, v[128:143]
	v_mfma_f32_32x32x2_f32 v[144:159], v231, v191, v[144:159]
	v_add_u32_e32 v232, v232, v236
	v_and_or_b32 v240, v232, s11, v244
	v_add_u32_e32 v233, v233, v237
	v_and_or_b32 v241, v233, s11, v244
	v_add_u32_e32 v234, v234, v238
	v_and_or_b32 v242, v234, s11, v244
	v_add_u32_e32 v235, v235, v239
	v_and_or_b32 v243, v235, s11, v244
	ds_read_b32 v228, v240
	ds_read_b32 v229, v241
	ds_read_b32 v230, v242
	ds_read_b32 v231, v243
	s_waitcnt vmcnt(7) lgkmcnt(4)
	v_mfma_f32_32x32x2_f32 v[96:111], v224, v192, v[96:111]
	v_mfma_f32_32x32x2_f32 v[112:127], v225, v192, v[112:127]
	v_mfma_f32_32x32x2_f32 v[128:143], v226, v192, v[128:143]
	v_mfma_f32_32x32x2_f32 v[144:159], v227, v192, v[144:159]
	v_add_u32_e32 v232, v232, v236
	v_and_or_b32 v240, v232, s11, v244
	v_add_u32_e32 v233, v233, v237
	v_and_or_b32 v241, v233, s11, v244
	v_add_u32_e32 v234, v234, v238
	v_and_or_b32 v242, v234, s11, v244
	v_add_u32_e32 v235, v235, v239
	v_and_or_b32 v243, v235, s11, v244
	ds_read_b32 v224, v240
	ds_read_b32 v225, v241
	ds_read_b32 v226, v242
	ds_read_b32 v227, v243
	s_waitcnt lgkmcnt(4)
	v_mfma_f32_32x32x2_f32 v[96:111], v228, v193, v[96:111]
	v_mfma_f32_32x32x2_f32 v[112:127], v229, v193, v[112:127]
	v_mfma_f32_32x32x2_f32 v[128:143], v230, v193, v[128:143]
	v_mfma_f32_32x32x2_f32 v[144:159], v231, v193, v[144:159]
	v_add_u32_e32 v232, v232, v236
	v_and_or_b32 v240, v232, s11, v244
	v_add_u32_e32 v233, v233, v237
	v_and_or_b32 v241, v233, s11, v244
	v_add_u32_e32 v234, v234, v238
	v_and_or_b32 v242, v234, s11, v244
	v_add_u32_e32 v235, v235, v239
	v_and_or_b32 v243, v235, s11, v244
	ds_read_b32 v228, v240
	ds_read_b32 v229, v241
	ds_read_b32 v230, v242
	ds_read_b32 v231, v243
	s_waitcnt lgkmcnt(4)
	v_mfma_f32_32x32x2_f32 v[96:111], v224, v194, v[96:111]
	v_mfma_f32_32x32x2_f32 v[112:127], v225, v194, v[112:127]
	v_mfma_f32_32x32x2_f32 v[128:143], v226, v194, v[128:143]
	v_mfma_f32_32x32x2_f32 v[144:159], v227, v194, v[144:159]
	v_add_u32_e32 v232, v232, v236
	v_and_or_b32 v240, v232, s11, v244
	v_add_u32_e32 v233, v233, v237
	v_and_or_b32 v241, v233, s11, v244
	v_add_u32_e32 v234, v234, v238
	v_and_or_b32 v242, v234, s11, v244
	v_add_u32_e32 v235, v235, v239
	v_and_or_b32 v243, v235, s11, v244
	ds_read_b32 v224, v240
	ds_read_b32 v225, v241
	ds_read_b32 v226, v242
	ds_read_b32 v227, v243
	s_waitcnt lgkmcnt(4)
	v_mfma_f32_32x32x2_f32 v[96:111], v228, v195, v[96:111]
	v_mfma_f32_32x32x2_f32 v[112:127], v229, v195, v[112:127]
	v_mfma_f32_32x32x2_f32 v[128:143], v230, v195, v[128:143]
	v_mfma_f32_32x32x2_f32 v[144:159], v231, v195, v[144:159]
	v_add_u32_e32 v232, v232, v236
	v_and_or_b32 v240, v232, s11, v244
	v_add_u32_e32 v233, v233, v237
	v_and_or_b32 v241, v233, s11, v244
	v_add_u32_e32 v234, v234, v238
	v_and_or_b32 v242, v234, s11, v244
	v_add_u32_e32 v235, v235, v239
	v_and_or_b32 v243, v235, s11, v244
	ds_read_b32 v228, v240
	ds_read_b32 v229, v241
	ds_read_b32 v230, v242
	ds_read_b32 v231, v243
	s_waitcnt vmcnt(6) lgkmcnt(4)
; __device__ __forceinline__ void p0a(Frame& F, const Args& AR) {
;     ...
;             for (int q = 0; q < 2; ++q) { const int jj = F.lane + 64 * q, mp = jj >> 1, odd = jj & 1;
;                 const int mult = mp == 0 ? (odd ? 64 : 0) : mp, shift = (mp != 0 && odd) ? 96 : 0; const float sgn = (mp != 0 && odd) ? -1.f : 1.f;
;                 float s = 0.f;
;                 for (int c = 0; c < 128; ++c) s += scr[128 + c] * scr[(mult * c + shift) & 127];
;                 wf[(size_t)ld * 512 + 128 * h + jj] = s * sgn; }
	v_mfma_f32_32x32x2_f32 v[96:111], v224, v196, v[96:111]
	v_mfma_f32_32x32x2_f32 v[112:127], v225, v196, v[112:127]
	v_mfma_f32_32x32x2_f32 v[128:143], v226, v196, v[128:143]
	v_mfma_f32_32x32x2_f32 v[144:159], v227, v196, v[144:159]
	v_add_u32_e32 v232, v232, v236
	v_and_or_b32 v240, v232, s11, v244
	v_add_u32_e32 v233, v233, v237
	v_and_or_b32 v241, v233, s11, v244
	v_add_u32_e32 v234, v234, v238
	v_and_or_b32 v242, v234, s11, v244
	v_add_u32_e32 v235, v235, v239
	v_and_or_b32 v243, v235, s11, v244
	ds_read_b32 v224, v240
	ds_read_b32 v225, v241
	ds_read_b32 v226, v242
	ds_read_b32 v227, v243
	s_waitcnt lgkmcnt(4)
	v_mfma_f32_32x32x2_f32 v[96:111], v228, v197, v[96:111]
	v_mfma_f32_32x32x2_f32 v[112:127], v229, v197, v[112:127]
	v_mfma_f32_32x32x2_f32 v[128:143], v230, v197, v[128:143]
	v_mfma_f32_32x32x2_f32 v[144:159], v231, v197, v[144:159]
	v_add_u32_e32 v232, v232, v236
	v_and_or_b32 v240, v232, s11, v244
	v_add_u32_e32 v233, v233, v237
	v_and_or_b32 v241, v233, s11, v244
	v_add_u32_e32 v234, v234, v238
	v_and_or_b32 v242, v234, s11, v244
	v_add_u32_e32 v235, v235, v239
	v_and_or_b32 v243, v235, s11, v244
	ds_read_b32 v228, v240
	ds_read_b32 v229, v241
	ds_read_b32 v230, v242
	ds_read_b32 v231, v243
	s_waitcnt lgkmcnt(4)
	v_mfma_f32_32x32x2_f32 v[96:111], v224, v198, v[96:111]
	v_mfma_f32_32x32x2_f32 v[112:127], v225, v198, v[112:127]
	v_mfma_f32_32x32x2_f32 v[128:143], v226, v198, v[128:143]
	v_mfma_f32_32x32x2_f32 v[144:159], v227, v198, v[144:159]
	v_add_u32_e32 v232, v232, v236
	v_and_or_b32 v240, v232, s11, v244
	v_add_u32_e32 v233, v233, v237
	v_and_or_b32 v241, v233, s11, v244
	v_add_u32_e32 v234, v234, v238
	v_and_or_b32 v242, v234, s11, v244
	v_add_u32_e32 v235, v235, v239
	v_and_or_b32 v243, v235, s11, v244
	ds_read_b32 v224, v240
	ds_read_b32 v225, v241
	ds_read_b32 v226, v242
	ds_read_b32 v227, v243
	s_waitcnt lgkmcnt(4)
	v_mfma_f32_32x32x2_f32 v[96:111], v228, v199, v[96:111]
	v_mfma_f32_32x32x2_f32 v[112:127], v229, v199, v[112:127]
	v_mfma_f32_32x32x2_f32 v[128:143], v230, v199, v[128:143]
	v_mfma_f32_32x32x2_f32 v[144:159], v231, v199, v[144:159]
	v_add_u32_e32 v232, v232, v236
	v_and_or_b32 v240, v232, s11, v244
	v_add_u32_e32 v233, v233, v237
	v_and_or_b32 v241, v233, s11, v244
	v_add_u32_e32 v234, v234, v238
	v_and_or_b32 v242, v234, s11, v244
	v_add_u32_e32 v235, v235, v239
	v_and_or_b32 v243, v235, s11, v244
	ds_read_b32 v228, v240
	ds_read_b32 v229, v241
	ds_read_b32 v230, v242
	ds_read_b32 v231, v243
	s_waitcnt vmcnt(5) lgkmcnt(4)
	v_mfma_f32_32x32x2_f32 v[96:111], v224, v200, v[96:111]
	v_mfma_f32_32x32x2_f32 v[112:127], v225, v200, v[112:127]
	v_mfma_f32_32x32x2_f32 v[128:143], v226, v200, v[128:143]
	v_mfma_f32_32x32x2_f32 v[144:159], v227, v200, v[144:159]
	v_add_u32_e32 v232, v232, v236
	v_and_or_b32 v240, v232, s11, v244
	v_add_u32_e32 v233, v233, v237
	v_and_or_b32 v241, v233, s11, v244
	v_add_u32_e32 v234, v234, v238
	v_and_or_b32 v242, v234, s11, v244
	v_add_u32_e32 v235, v235, v239
	v_and_or_b32 v243, v235, s11, v244
	ds_read_b32 v224, v240
	ds_read_b32 v225, v241
	ds_read_b32 v226, v242
	ds_read_b32 v227, v243
	s_waitcnt lgkmcnt(4)
	v_mfma_f32_32x32x2_f32 v[96:111], v228, v201, v[96:111]
	v_mfma_f32_32x32x2_f32 v[112:127], v229, v201, v[112:127]
	v_mfma_f32_32x32x2_f32 v[128:143], v230, v201, v[128:143]
	v_mfma_f32_32x32x2_f32 v[144:159], v231, v201, v[144:159]
	v_add_u32_e32 v232, v232, v236
	v_and_or_b32 v240, v232, s11, v244
	v_add_u32_e32 v233, v233, v237
	v_and_or_b32 v241, v233, s11, v244
	v_add_u32_e32 v234, v234, v238
	v_and_or_b32 v242, v234, s11, v244
	v_add_u32_e32 v235, v235, v239
	v_and_or_b32 v243, v235, s11, v244
	ds_read_b32 v228, v240
	ds_read_b32 v229, v241
	ds_read_b32 v230, v242
	ds_read_b32 v231, v243
	s_waitcnt lgkmcnt(4)
	v_mfma_f32_32x32x2_f32 v[96:111], v224, v202, v[96:111]
	v_mfma_f32_32x32x2_f32 v[112:127], v225, v202, v[112:127]
	v_mfma_f32_32x32x2_f32 v[128:143], v226, v202, v[128:143]
	v_mfma_f32_32x32x2_f32 v[144:159], v227, v202, v[144:159]
	v_add_u32_e32 v232, v232, v236
	v_and_or_b32 v240, v232, s11, v244
	v_add_u32_e32 v233, v233, v237
	v_and_or_b32 v241, v233, s11, v244
	v_add_u32_e32 v234, v234, v238
	v_and_or_b32 v242, v234, s11, v244
	v_add_u32_e32 v235, v235, v239
	v_and_or_b32 v243, v235, s11, v244
	ds_read_b32 v224, v240
	ds_read_b32 v225, v241
	ds_read_b32 v226, v242
	ds_read_b32 v227, v243
	s_waitcnt lgkmcnt(4)
	v_mfma_f32_32x32x2_f32 v[96:111], v228, v203, v[96:111]
	v_mfma_f32_32x32x2_f32 v[112:127], v229, v203, v[112:127]
	v_mfma_f32_32x32x2_f32 v[128:143], v230, v203, v[128:143]
	v_mfma_f32_32x32x2_f32 v[144:159], v231, v203, v[144:159]
	v_add_u32_e32 v232, v232, v236
	v_and_or_b32 v240, v232, s11, v244
	v_add_u32_e32 v233, v233, v237
	v_and_or_b32 v241, v233, s11, v244
	v_add_u32_e32 v234, v234, v238
	v_and_or_b32 v242, v234, s11, v244
	v_add_u32_e32 v235, v235, v239
	v_and_or_b32 v243, v235, s11, v244
	ds_read_b32 v228, v240
	ds_read_b32 v229, v241
	ds_read_b32 v230, v242
	ds_read_b32 v231, v243
	s_waitcnt vmcnt(4) lgkmcnt(4)
	v_mfma_f32_32x32x2_f32 v[96:111], v224, v204, v[96:111]
	v_mfma_f32_32x32x2_f32 v[112:127], v225, v204, v[112:127]
	v_mfma_f32_32x32x2_f32 v[128:143], v226, v204, v[128:143]
	v_mfma_f32_32x32x2_f32 v[144:159], v227, v204, v[144:159]
	v_add_u32_e32 v232, v232, v236
	v_and_or_b32 v240, v232, s11, v244
	v_add_u32_e32 v233, v233, v237
	v_and_or_b32 v241, v233, s11, v244
	v_add_u32_e32 v234, v234, v238
	v_and_or_b32 v242, v234, s11, v244
	v_add_u32_e32 v235, v235, v239
	v_and_or_b32 v243, v235, s11, v244
	ds_read_b32 v224, v240
	ds_read_b32 v225, v241
	ds_read_b32 v226, v242
	ds_read_b32 v227, v243
	s_waitcnt lgkmcnt(4)
; __device__ __forceinline__ void p0a(Frame& F, const Args& AR) {
;     ...
;             for (int q = 0; q < 2; ++q) { const int jj = F.lane + 64 * q, mp = jj >> 1, odd = jj & 1;
;                 const int mult = mp == 0 ? (odd ? 64 : 0) : mp, shift = (mp != 0 && odd) ? 96 : 0; const float sgn = (mp != 0 && odd) ? -1.f : 1.f;
;                 float s = 0.f;
;                 for (int c = 0; c < 128; ++c) s += scr[128 + c] * scr[(mult * c + shift) & 127];
;                 wf[(size_t)ld * 512 + 128 * h + jj] = s * sgn; }
	v_mfma_f32_32x32x2_f32 v[96:111], v228, v205, v[96:111]
	v_mfma_f32_32x32x2_f32 v[112:127], v229, v205, v[112:127]
	v_mfma_f32_32x32x2_f32 v[128:143], v230, v205, v[128:143]
	v_mfma_f32_32x32x2_f32 v[144:159], v231, v205, v[144:159]
	v_add_u32_e32 v232, v232, v236
	v_and_or_b32 v240, v232, s11, v244
	v_add_u32_e32 v233, v233, v237
	v_and_or_b32 v241, v233, s11, v244
	v_add_u32_e32 v234, v234, v238
	v_and_or_b32 v242, v234, s11, v244
	v_add_u32_e32 v235, v235, v239
	v_and_or_b32 v243, v235, s11, v244
	ds_read_b32 v228, v240
	ds_read_b32 v229, v241
	ds_read_b32 v230, v242
	ds_read_b32 v231, v243
	s_waitcnt lgkmcnt(4)
	v_mfma_f32_32x32x2_f32 v[96:111], v224, v206, v[96:111]
	v_mfma_f32_32x32x2_f32 v[112:127], v225, v206, v[112:127]
	v_mfma_f32_32x32x2_f32 v[128:143], v226, v206, v[128:143]
	v_mfma_f32_32x32x2_f32 v[144:159], v227, v206, v[144:159]
	v_add_u32_e32 v232, v232, v236
	v_and_or_b32 v240, v232, s11, v244
	v_add_u32_e32 v233, v233, v237
	v_and_or_b32 v241, v233, s11, v244
	v_add_u32_e32 v234, v234, v238
	v_and_or_b32 v242, v234, s11, v244
	v_add_u32_e32 v235, v235, v239
	v_and_or_b32 v243, v235, s11, v244
	ds_read_b32 v224, v240
	ds_read_b32 v225, v241
	ds_read_b32 v226, v242
	ds_read_b32 v227, v243
	s_waitcnt lgkmcnt(4)
	v_mfma_f32_32x32x2_f32 v[96:111], v228, v207, v[96:111]
	v_mfma_f32_32x32x2_f32 v[112:127], v229, v207, v[112:127]
	v_mfma_f32_32x32x2_f32 v[128:143], v230, v207, v[128:143]
	v_mfma_f32_32x32x2_f32 v[144:159], v231, v207, v[144:159]
	v_add_u32_e32 v232, v232, v236
	v_and_or_b32 v240, v232, s11, v244
	v_add_u32_e32 v233, v233, v237
	v_and_or_b32 v241, v233, s11, v244
	v_add_u32_e32 v234, v234, v238
	v_and_or_b32 v242, v234, s11, v244
	v_add_u32_e32 v235, v235, v239
	v_and_or_b32 v243, v235, s11, v244
	ds_read_b32 v228, v240
	ds_read_b32 v229, v241
	ds_read_b32 v230, v242
	ds_read_b32 v231, v243
	s_waitcnt vmcnt(3) lgkmcnt(4)
	v_mfma_f32_32x32x2_f32 v[96:111], v224, v208, v[96:111]
	v_mfma_f32_32x32x2_f32 v[112:127], v225, v208, v[112:127]
	v_mfma_f32_32x32x2_f32 v[128:143], v226, v208, v[128:143]
	v_mfma_f32_32x32x2_f32 v[144:159], v227, v208, v[144:159]
	v_add_u32_e32 v232, v232, v236
	v_and_or_b32 v240, v232, s11, v244
	v_add_u32_e32 v233, v233, v237
	v_and_or_b32 v241, v233, s11, v244
	v_add_u32_e32 v234, v234, v238
	v_and_or_b32 v242, v234, s11, v244
	v_add_u32_e32 v235, v235, v239
	v_and_or_b32 v243, v235, s11, v244
	ds_read_b32 v224, v240
	ds_read_b32 v225, v241
	ds_read_b32 v226, v242
	ds_read_b32 v227, v243
	s_waitcnt lgkmcnt(4)
	v_mfma_f32_32x32x2_f32 v[96:111], v228, v209, v[96:111]
	v_mfma_f32_32x32x2_f32 v[112:127], v229, v209, v[112:127]
	v_mfma_f32_32x32x2_f32 v[128:143], v230, v209, v[128:143]
	v_mfma_f32_32x32x2_f32 v[144:159], v231, v209, v[144:159]
	v_add_u32_e32 v232, v232, v236
	v_and_or_b32 v240, v232, s11, v244
	v_add_u32_e32 v233, v233, v237
	v_and_or_b32 v241, v233, s11, v244
	v_add_u32_e32 v234, v234, v238
	v_and_or_b32 v242, v234, s11, v244
	v_add_u32_e32 v235, v235, v239
	v_and_or_b32 v243, v235, s11, v244
	ds_read_b32 v228, v240
	ds_read_b32 v229, v241
	ds_read_b32 v230, v242
	ds_read_b32 v231, v243
	s_waitcnt lgkmcnt(4)
	v_mfma_f32_32x32x2_f32 v[96:111], v224, v210, v[96:111]
	v_mfma_f32_32x32x2_f32 v[112:127], v225, v210, v[112:127]
	v_mfma_f32_32x32x2_f32 v[128:143], v226, v210, v[128:143]
	v_mfma_f32_32x32x2_f32 v[144:159], v227, v210, v[144:159]
	v_add_u32_e32 v232, v232, v236
	v_and_or_b32 v240, v232, s11, v244
	v_add_u32_e32 v233, v233, v237
	v_and_or_b32 v241, v233, s11, v244
	v_add_u32_e32 v234, v234, v238
	v_and_or_b32 v242, v234, s11, v244
	v_add_u32_e32 v235, v235, v239
	v_and_or_b32 v243, v235, s11, v244
	ds_read_b32 v224, v240
	ds_read_b32 v225, v241
	ds_read_b32 v226, v242
	ds_read_b32 v227, v243
	s_waitcnt lgkmcnt(4)
	v_mfma_f32_32x32x2_f32 v[96:111], v228, v211, v[96:111]
	v_mfma_f32_32x32x2_f32 v[112:127], v229, v211, v[112:127]
	v_mfma_f32_32x32x2_f32 v[128:143], v230, v211, v[128:143]
	v_mfma_f32_32x32x2_f32 v[144:159], v231, v211, v[144:159]
	v_add_u32_e32 v232, v232, v236
	v_and_or_b32 v240, v232, s11, v244
	v_add_u32_e32 v233, v233, v237
	v_and_or_b32 v241, v233, s11, v244
	v_add_u32_e32 v234, v234, v238
	v_and_or_b32 v242, v234, s11, v244
	v_add_u32_e32 v235, v235, v239
	v_and_or_b32 v243, v235, s11, v244
	ds_read_b32 v228, v240
	ds_read_b32 v229, v241
	ds_read_b32 v230, v242
	ds_read_b32 v231, v243
	s_waitcnt vmcnt(2) lgkmcnt(4)
	v_mfma_f32_32x32x2_f32 v[96:111], v224, v212, v[96:111]
	v_mfma_f32_32x32x2_f32 v[112:127], v225, v212, v[112:127]
	v_mfma_f32_32x32x2_f32 v[128:143], v226, v212, v[128:143]
	v_mfma_f32_32x32x2_f32 v[144:159], v227, v212, v[144:159]
	v_add_u32_e32 v232, v232, v236
	v_and_or_b32 v240, v232, s11, v244
	v_add_u32_e32 v233, v233, v237
	v_and_or_b32 v241, v233, s11, v244
	v_add_u32_e32 v234, v234, v238
	v_and_or_b32 v242, v234, s11, v244
	v_add_u32_e32 v235, v235, v239
	v_and_or_b32 v243, v235, s11, v244
	ds_read_b32 v224, v240
	ds_read_b32 v225, v241
	ds_read_b32 v226, v242
	ds_read_b32 v227, v243
	s_waitcnt lgkmcnt(4)
	v_mfma_f32_32x32x2_f32 v[96:111], v228, v213, v[96:111]
	v_mfma_f32_32x32x2_f32 v[112:127], v229, v213, v[112:127]
	v_mfma_f32_32x32x2_f32 v[128:143], v230, v213, v[128:143]
	v_mfma_f32_32x32x2_f32 v[144:159], v231, v213, v[144:159]
	v_add_u32_e32 v232, v232, v236
	v_and_or_b32 v240, v232, s11, v244
	v_add_u32_e32 v233, v233, v237
	v_and_or_b32 v241, v233, s11, v244
	v_add_u32_e32 v234, v234, v238
	v_and_or_b32 v242, v234, s11, v244
	v_add_u32_e32 v235, v235, v239
	v_and_or_b32 v243, v235, s11, v244
	ds_read_b32 v228, v240
	ds_read_b32 v229, v241
	ds_read_b32 v230, v242
	ds_read_b32 v231, v243
	s_waitcnt lgkmcnt(4)
; #define LDS_WAIT() asm volatile("s_waitcnt lgkmcnt(0)" ::: "memory")
; __device__ __forceinline__ void p0a(Frame& F, const Args& AR) {
;     ...
;         for (int it = gw; it < DEPTH * DM * 4; it += NGW) {
;             const int h = it & 3, ld = it >> 2;
;             const float* src = AR.in[I_WIN] + (size_t)ld * DIN + FFT_OFF + 128 * h;
;             LDS_WAIT(); asm volatile("" ::: "memory");
;             scr[128 + F.lane] = src[F.lane]; scr[192 + F.lane] = src[F.lane + 64];
;             LDS_WAIT(); asm volatile("" ::: "memory");
; #pragma unroll
;             for (int q = 0; q < 2; ++q) { const int jj = F.lane + 64 * q, mp = jj >> 1, odd = jj & 1;
;                 const int mult = mp == 0 ? (odd ? 64 : 0) : mp, shift = (mp != 0 && odd) ? 96 : 0; const float sgn = (mp != 0 && odd) ? -1.f : 1.f;
;                 float s = 0.f;
;                 for (int c = 0; c < 128; ++c) s += scr[128 + c] * scr[(mult * c + shift) & 127];
;                 wf[(size_t)ld * 512 + 128 * h + jj] = s * sgn; }
	v_mfma_f32_32x32x2_f32 v[96:111], v224, v214, v[96:111]
	v_mfma_f32_32x32x2_f32 v[112:127], v225, v214, v[112:127]
	v_mfma_f32_32x32x2_f32 v[128:143], v226, v214, v[128:143]
	v_mfma_f32_32x32x2_f32 v[144:159], v227, v214, v[144:159]
	v_add_u32_e32 v232, v232, v236
	v_and_or_b32 v240, v232, s11, v244
	v_add_u32_e32 v233, v233, v237
	v_and_or_b32 v241, v233, s11, v244
	v_add_u32_e32 v234, v234, v238
	v_and_or_b32 v242, v234, s11, v244
	v_add_u32_e32 v235, v235, v239
	v_and_or_b32 v243, v235, s11, v244
	ds_read_b32 v224, v240
	ds_read_b32 v225, v241
	ds_read_b32 v226, v242
	ds_read_b32 v227, v243
	s_waitcnt lgkmcnt(4)
	v_mfma_f32_32x32x2_f32 v[96:111], v228, v215, v[96:111]
	v_mfma_f32_32x32x2_f32 v[112:127], v229, v215, v[112:127]
	v_mfma_f32_32x32x2_f32 v[128:143], v230, v215, v[128:143]
	v_mfma_f32_32x32x2_f32 v[144:159], v231, v215, v[144:159]
	v_add_u32_e32 v232, v232, v236
	v_and_or_b32 v240, v232, s11, v244
	v_add_u32_e32 v233, v233, v237
	v_and_or_b32 v241, v233, s11, v244
	v_add_u32_e32 v234, v234, v238
	v_and_or_b32 v242, v234, s11, v244
	v_add_u32_e32 v235, v235, v239
	v_and_or_b32 v243, v235, s11, v244
	ds_read_b32 v228, v240
	ds_read_b32 v229, v241
	ds_read_b32 v230, v242
	ds_read_b32 v231, v243
	s_waitcnt vmcnt(1) lgkmcnt(4)
	v_mfma_f32_32x32x2_f32 v[96:111], v224, v216, v[96:111]
	v_mfma_f32_32x32x2_f32 v[112:127], v225, v216, v[112:127]
	v_mfma_f32_32x32x2_f32 v[128:143], v226, v216, v[128:143]
	v_mfma_f32_32x32x2_f32 v[144:159], v227, v216, v[144:159]
	v_add_u32_e32 v232, v232, v236
	v_and_or_b32 v240, v232, s11, v244
	v_add_u32_e32 v233, v233, v237
	v_and_or_b32 v241, v233, s11, v244
	v_add_u32_e32 v234, v234, v238
	v_and_or_b32 v242, v234, s11, v244
	v_add_u32_e32 v235, v235, v239
	v_and_or_b32 v243, v235, s11, v244
	ds_read_b32 v224, v240
	ds_read_b32 v225, v241
	ds_read_b32 v226, v242
	ds_read_b32 v227, v243
	s_waitcnt lgkmcnt(4)
	v_mfma_f32_32x32x2_f32 v[96:111], v228, v217, v[96:111]
	v_mfma_f32_32x32x2_f32 v[112:127], v229, v217, v[112:127]
	v_mfma_f32_32x32x2_f32 v[128:143], v230, v217, v[128:143]
	v_mfma_f32_32x32x2_f32 v[144:159], v231, v217, v[144:159]
	v_add_u32_e32 v232, v232, v236
	v_and_or_b32 v240, v232, s11, v244
	v_add_u32_e32 v233, v233, v237
	v_and_or_b32 v241, v233, s11, v244
	v_add_u32_e32 v234, v234, v238
	v_and_or_b32 v242, v234, s11, v244
	v_add_u32_e32 v235, v235, v239
	v_and_or_b32 v243, v235, s11, v244
	ds_read_b32 v228, v240
	ds_read_b32 v229, v241
	ds_read_b32 v230, v242
	ds_read_b32 v231, v243
	s_waitcnt lgkmcnt(4)
	v_mfma_f32_32x32x2_f32 v[96:111], v224, v218, v[96:111]
	v_mfma_f32_32x32x2_f32 v[112:127], v225, v218, v[112:127]
	v_mfma_f32_32x32x2_f32 v[128:143], v226, v218, v[128:143]
	v_mfma_f32_32x32x2_f32 v[144:159], v227, v218, v[144:159]
	v_add_u32_e32 v232, v232, v236
	v_and_or_b32 v240, v232, s11, v244
	v_add_u32_e32 v233, v233, v237
	v_and_or_b32 v241, v233, s11, v244
	v_add_u32_e32 v234, v234, v238
	v_and_or_b32 v242, v234, s11, v244
	v_add_u32_e32 v235, v235, v239
	v_and_or_b32 v243, v235, s11, v244
	ds_read_b32 v224, v240
	ds_read_b32 v225, v241
	ds_read_b32 v226, v242
	ds_read_b32 v227, v243
	s_waitcnt lgkmcnt(4)
	v_mfma_f32_32x32x2_f32 v[96:111], v228, v219, v[96:111]
	v_mfma_f32_32x32x2_f32 v[112:127], v229, v219, v[112:127]
	v_mfma_f32_32x32x2_f32 v[128:143], v230, v219, v[128:143]
	v_mfma_f32_32x32x2_f32 v[144:159], v231, v219, v[144:159]
	v_add_u32_e32 v232, v232, v236
	v_and_or_b32 v240, v232, s11, v244
	v_add_u32_e32 v233, v233, v237
	v_and_or_b32 v241, v233, s11, v244
	v_add_u32_e32 v234, v234, v238
	v_and_or_b32 v242, v234, s11, v244
	v_add_u32_e32 v235, v235, v239
	v_and_or_b32 v243, v235, s11, v244
	ds_read_b32 v228, v240
	ds_read_b32 v229, v241
	ds_read_b32 v230, v242
	ds_read_b32 v231, v243
	s_waitcnt vmcnt(0) lgkmcnt(4)
	v_mfma_f32_32x32x2_f32 v[96:111], v224, v220, v[96:111]
	v_mfma_f32_32x32x2_f32 v[112:127], v225, v220, v[112:127]
	v_mfma_f32_32x32x2_f32 v[128:143], v226, v220, v[128:143]
	v_mfma_f32_32x32x2_f32 v[144:159], v227, v220, v[144:159]
	v_add_u32_e32 v232, v232, v236
	v_and_or_b32 v240, v232, s11, v244
	v_add_u32_e32 v233, v233, v237
	v_and_or_b32 v241, v233, s11, v244
	v_add_u32_e32 v234, v234, v238
	v_and_or_b32 v242, v234, s11, v244
	v_add_u32_e32 v235, v235, v239
	v_and_or_b32 v243, v235, s11, v244
	ds_read_b32 v224, v240
	ds_read_b32 v225, v241
	ds_read_b32 v226, v242
	ds_read_b32 v227, v243
	s_waitcnt lgkmcnt(4)
	v_mfma_f32_32x32x2_f32 v[96:111], v228, v221, v[96:111]
	v_mfma_f32_32x32x2_f32 v[112:127], v229, v221, v[112:127]
	v_mfma_f32_32x32x2_f32 v[128:143], v230, v221, v[128:143]
	v_mfma_f32_32x32x2_f32 v[144:159], v231, v221, v[144:159]
	v_add_u32_e32 v232, v232, v236
	v_and_or_b32 v240, v232, s11, v244
	v_add_u32_e32 v233, v233, v237
	v_and_or_b32 v241, v233, s11, v244
	v_add_u32_e32 v234, v234, v238
	v_and_or_b32 v242, v234, s11, v244
	v_add_u32_e32 v235, v235, v239
	v_and_or_b32 v243, v235, s11, v244
	ds_read_b32 v228, v240
	ds_read_b32 v229, v241
	ds_read_b32 v230, v242
	ds_read_b32 v231, v243
	s_waitcnt lgkmcnt(4)
	v_mfma_f32_32x32x2_f32 v[96:111], v224, v222, v[96:111]
	v_mfma_f32_32x32x2_f32 v[112:127], v225, v222, v[112:127]
	v_mfma_f32_32x32x2_f32 v[128:143], v226, v222, v[128:143]
	v_mfma_f32_32x32x2_f32 v[144:159], v227, v222, v[144:159]
	s_waitcnt lgkmcnt(0)
	v_mfma_f32_32x32x2_f32 v[96:111], v228, v223, v[96:111]
	v_mfma_f32_32x32x2_f32 v[112:127], v229, v223, v[112:127]
	v_mfma_f32_32x32x2_f32 v[128:143], v230, v223, v[128:143]
	v_mfma_f32_32x32x2_f32 v[144:159], v231, v223, v[144:159]
	s_nop 15
	s_nop 15
	global_store_dwordx4 v[248:249], v[96:99], off
	global_store_dwordx4 v[248:249], v[100:103], off offset:32
	global_store_dwordx4 v[248:249], v[104:107], off offset:64
	global_store_dwordx4 v[248:249], v[108:111], off offset:96
	global_store_dwordx4 v[248:249], v[112:115], off offset:128
	global_store_dwordx4 v[248:249], v[116:119], off offset:160
	global_store_dwordx4 v[248:249], v[120:123], off offset:192
	global_store_dwordx4 v[248:249], v[124:127], off offset:224
	global_store_dwordx4 v[248:249], v[128:131], off offset:256
	global_store_dwordx4 v[248:249], v[132:135], off offset:288
	global_store_dwordx4 v[248:249], v[136:139], off offset:320
	global_store_dwordx4 v[248:249], v[140:143], off offset:352
	global_store_dwordx4 v[248:249], v[144:147], off offset:384
	global_store_dwordx4 v[248:249], v[148:151], off offset:416
	global_store_dwordx4 v[248:249], v[152:155], off offset:448
	global_store_dwordx4 v[248:249], v[156:159], off offset:480
